# attention tile-drop test: scalar mul/fma instead of packed f32 ops; one SALU add in the position preamble
# baseline (speedup 1.0000x reference)
.LBB0_1380:
	v_mov_b32_e32 v248, s13
	ds_read2_b32 v[248:249], v248 offset0:1 offset1:129
	ds_read_b128 v[232:235], v222
	ds_read_b128 v[146:149], v222 offset:32
	ds_read_b128 v[236:239], v222 offset:8704
	ds_read_b128 v[150:153], v222 offset:8736
	ds_read_b128 v[154:157], v222 offset:64
	ds_read_b128 v[158:161], v222 offset:96
	ds_read_b128 v[162:165], v222 offset:8768
	ds_read_b128 v[228:231], v222 offset:8800
	s_add_i32 s7, s12, 0xc0
	v_add_u32_e32 v184, s7, v223
	v_cvt_f32_i32_e32 v185, v184
	v_mul_f32_e64 v245, -v201, v185
	v_sub_f32_e32 v246, v245, v226
	v_mov_b32_e32 v82, v246
	v_fmamk_f32 v83, v201, 0x3f800000, v246
	v_fmamk_f32 v84, v201, 0x40000000, v246
	v_fmamk_f32 v85, v201, 0x40400000, v246
	v_fmamk_f32 v86, v201, 0x41000000, v246
	v_fmamk_f32 v87, v201, 0x41100000, v246
	v_fmamk_f32 v88, v201, 0x41200000, v246
	v_fmamk_f32 v89, v201, 0x41300000, v246
	v_fmamk_f32 v90, v201, 0x41800000, v246
	v_fmamk_f32 v91, v201, 0x41880000, v246
	v_fmamk_f32 v92, v201, 0x41900000, v246
	v_fmamk_f32 v93, v201, 0x41980000, v246
	v_fmamk_f32 v94, v201, 0x41c00000, v246
	v_fmamk_f32 v95, v201, 0x41c80000, v246
	v_fmamk_f32 v96, v201, 0x41d00000, v246
	v_fmamk_f32 v97, v201, 0x41d80000, v246
	v_fmamk_f32 v66, v201, 0x42000000, v246
	v_fmamk_f32 v67, v201, 0x42040000, v246
	v_fmamk_f32 v68, v201, 0x42080000, v246
	v_fmamk_f32 v69, v201, 0x420c0000, v246
	v_fmamk_f32 v70, v201, 0x42200000, v246
	v_fmamk_f32 v71, v201, 0x42240000, v246
	v_fmamk_f32 v72, v201, 0x42280000, v246
	v_fmamk_f32 v73, v201, 0x422c0000, v246
	v_fmamk_f32 v74, v201, 0x42400000, v246
	v_fmamk_f32 v75, v201, 0x42440000, v246
	v_fmamk_f32 v76, v201, 0x42480000, v246
	v_fmamk_f32 v77, v201, 0x424c0000, v246
	v_fmamk_f32 v78, v201, 0x42600000, v246
	v_fmamk_f32 v79, v201, 0x42640000, v246
	v_fmamk_f32 v80, v201, 0x42680000, v246
	v_fmamk_f32 v81, v201, 0x426c0000, v246
	s_add_i32 s46, s35, -1
	s_cmp_ge_i32 s46, s26
	s_cbranch_scc1 .LBB0_1384
	s_add_i32 s0, s12, s27
	s_addk_i32 s0, 0x140
	v_cvt_f32_i32_e32 v251, s0
	s_waitcnt lgkmcnt(8)
	v_mul_f32_e32 v250, v200, v249
	v_mul_f32_e32 v251, v201, v251
	v_fma_f32 v252, v178, v248, -v251
	v_sub_f32_e32 v250, v250, v251
	v_cmp_lt_f32_e32 vcc, v252, v180
	v_cmp_lt_f32_e64 s[0:1], v250, v181
	s_and_b64 s[0:1], vcc, s[0:1]
	s_and_b64 vcc, exec, s[0:1]
	s_mov_b32 s0, s46
	s_cbranch_vccnz .LBB0_1383
	s_add_i32 s0, s6, 1
	s_ashr_i32 s1, s0, 31
	s_lshl_b64 s[0:1], s[0:1], 14
	v_lshl_add_u64 v[250:251], v[196:197], 0, s[0:1]
	v_add_co_u32_e32 v252, vcc, 0x2000, v250
	v_lshl_add_u64 v[248:249], v[198:199], 0, s[0:1]
	s_nop 0
	v_addc_co_u32_e32 v253, vcc, 0, v251, vcc
	global_load_dwordx4 v[98:101], v[250:251], off
	global_load_dwordx4 v[102:105], v[252:253], off
	global_load_dwordx4 v[106:109], v[248:249], off
	v_add_co_u32_e32 v248, vcc, 0x2000, v248
	s_mov_b32 s0, s26
	s_nop 0
	v_addc_co_u32_e32 v249, vcc, 0, v249, vcc
	global_load_dwordx4 v[110:113], v[248:249], off

.LBB0_1390:
	s_andn2_b64 vcc, exec, s[0:1]
	s_waitcnt lgkmcnt(0)
	s_barrier
	s_cbranch_vccnz .LBB0_1396
	v_mov_b32_e32 v248, s13
	ds_read2st64_b32 v[248:249], v248 offset1:2
	ds_read_b128 v[232:235], v222 offset:35840
	ds_read_b128 v[146:149], v222 offset:35872
	ds_read_b128 v[236:239], v222 offset:44544
	ds_read_b128 v[150:153], v222 offset:44576
	ds_read_b128 v[154:157], v222 offset:35904
	ds_read_b128 v[158:161], v222 offset:35936
	ds_read_b128 v[162:165], v222 offset:44608
	ds_read_b128 v[228:231], v222 offset:44640
	s_add_i32 s7, s12, 0x100
	v_add_u32_e32 v184, s7, v223
	v_cvt_f32_i32_e32 v185, v184
	v_mul_f32_e64 v245, -v201, v185
	v_sub_f32_e32 v246, v245, v226
	v_mov_b32_e32 v82, v246
	v_fmamk_f32 v83, v201, 0x3f800000, v246
	v_fmamk_f32 v84, v201, 0x40000000, v246
	v_fmamk_f32 v85, v201, 0x40400000, v246
	v_fmamk_f32 v86, v201, 0x41000000, v246
	v_fmamk_f32 v87, v201, 0x41100000, v246
	v_fmamk_f32 v88, v201, 0x41200000, v246
	v_fmamk_f32 v89, v201, 0x41300000, v246
	v_fmamk_f32 v90, v201, 0x41800000, v246
	v_fmamk_f32 v91, v201, 0x41880000, v246
	v_fmamk_f32 v92, v201, 0x41900000, v246
	v_fmamk_f32 v93, v201, 0x41980000, v246
	v_fmamk_f32 v94, v201, 0x41c00000, v246
	v_fmamk_f32 v95, v201, 0x41c80000, v246
	v_fmamk_f32 v96, v201, 0x41d00000, v246
	v_fmamk_f32 v97, v201, 0x41d80000, v246
	v_fmamk_f32 v66, v201, 0x42000000, v246
	v_fmamk_f32 v67, v201, 0x42040000, v246
	v_fmamk_f32 v68, v201, 0x42080000, v246
	v_fmamk_f32 v69, v201, 0x420c0000, v246
	v_fmamk_f32 v70, v201, 0x42200000, v246
	v_fmamk_f32 v71, v201, 0x42240000, v246
	v_fmamk_f32 v72, v201, 0x42280000, v246
	v_fmamk_f32 v73, v201, 0x422c0000, v246
	v_fmamk_f32 v74, v201, 0x42400000, v246
	v_fmamk_f32 v75, v201, 0x42440000, v246
	v_fmamk_f32 v76, v201, 0x42480000, v246
	v_fmamk_f32 v77, v201, 0x424c0000, v246
	v_fmamk_f32 v78, v201, 0x42600000, v246
	v_fmamk_f32 v79, v201, 0x42640000, v246
	v_fmamk_f32 v80, v201, 0x42680000, v246
	v_fmamk_f32 v81, v201, 0x426c0000, v246
	s_cmp_ge_i32 s35, s26
	s_cbranch_scc1 .LBB0_1397
	s_add_i32 s0, s12, s27
	s_addk_i32 s0, 0x180
	v_cvt_f32_i32_e32 v250, s0
	s_waitcnt lgkmcnt(8)
	v_mul_f32_e32 v252, v201, v250
	v_fma_f32 v250, v178, v248, -v252
	v_fma_f32 v251, v179, v249, -v252
	v_cmp_lt_f32_e32 vcc, v251, v181
	v_cmp_lt_f32_e64 s[0:1], v250, v180
	s_and_b64 s[0:1], s[0:1], vcc
	s_and_b64 vcc, exec, s[0:1]
	s_mov_b32 s0, s35
	s_cbranch_vccnz .LBB0_1394
	s_ashr_i32 s7, s6, 31
	s_lshl_b64 s[0:1], s[6:7], 14
	v_lshl_add_u64 v[250:251], v[196:197], 0, s[0:1]
	v_add_co_u32_e32 v252, vcc, 0x2000, v250
	v_lshl_add_u64 v[248:249], v[198:199], 0, s[0:1]
	s_nop 0
	v_addc_co_u32_e32 v253, vcc, 0, v251, vcc
	global_load_dwordx4 v[114:117], v[250:251], off
	global_load_dwordx4 v[118:121], v[252:253], off
	global_load_dwordx4 v[122:125], v[248:249], off
	v_add_co_u32_e32 v248, vcc, 0x2000, v248
	s_mov_b32 s0, s26
	s_nop 0
	v_addc_co_u32_e32 v249, vcc, 0, v249, vcc
	global_load_dwordx4 v[126:129], v[248:249], off
